# placement: whole instruction stream shifted by 32 bytes (8 s_nop at entry) on v30
# speedup vs baseline: 1.0017x; 1.0017x over previous
_Z14fwd_megakernel6Params:
	s_nop 0
	s_nop 0
	s_nop 0
	s_nop 0
	s_nop 0
	s_nop 0
	s_nop 0
	s_nop 0
	s_load_dwordx2 s[24:25], s[0:1], 0xa8
	s_add_u32 s16, s0, 0xa8
	s_addc_u32 s17, s1, 0
	s_mov_b32 s77, s2
	s_waitcnt lgkmcnt(0)
	s_and_b32 s3, s24, 7
	s_cmp_lg_u32 s3, 0
	s_cbranch_scc0 .LBB0_10
	v_and_b32_e32 v224, 0x3ff, v0
	v_cmp_gt_u32_e32 vcc, 2, v224
	s_and_saveexec_b64 s[4:5], vcc
